# ping-pong v7 + near-diagonal (bias) tiles join the nop-free COMPUTE schedule and its in-gap pre-barrier work
# speedup vs baseline: 1.0065x; 1.0006x over previous
.Lpp_m9:
	v_mfma_f32_32x32x16_bf16 v[34:49], v[4:7], v[152:155], v[34:49]
	v_exp_f32_e32 v76, v76
	v_exp_f32_e32 v77, v77
	v_exp_f32_e32 v78, v78
	v_mfma_f32_32x32x16_bf16 v[18:33], v[4:7], v[168:171], v[18:33]
	v_exp_f32_e32 v79, v79
	v_exp_f32_e32 v80, v80
	v_exp_f32_e32 v81, v81
	v_mfma_f32_32x32x16_bf16 v[50:65], v[4:7], v[226:229], v[50:65]
	v_cvt_pk_bf16_f32 v8, v74, v75
	v_cvt_pk_bf16_f32 v9, v76, v77
	v_cvt_pk_bf16_f32 v10, v78, v79
	v_cvt_pk_bf16_f32 v11, v80, v81
	v_exp_f32_e32 v82, v82
	v_exp_f32_e32 v83, v83
	v_mfma_f32_32x32x16_bf16 v[34:49], v[8:11], v[156:159], v[34:49]
	v_exp_f32_e32 v84, v84
	v_exp_f32_e32 v85, v85
	v_exp_f32_e32 v86, v86
	v_mfma_f32_32x32x16_bf16 v[18:33], v[8:11], v[172:175], v[18:33]
	v_exp_f32_e32 v87, v87
	v_exp_f32_e32 v88, v88
	v_exp_f32_e32 v89, v89
	v_mfma_f32_32x32x16_bf16 v[50:65], v[8:11], v[226:229], v[50:65]
	v_cvt_pk_bf16_f32 v12, v82, v83
	v_cvt_pk_bf16_f32 v13, v84, v85
	v_cvt_pk_bf16_f32 v14, v86, v87
	v_cvt_pk_bf16_f32 v15, v88, v89
	v_exp_f32_e32 v90, v90
	v_exp_f32_e32 v91, v91
	v_mfma_f32_32x32x16_bf16 v[34:49], v[12:15], v[160:163], v[34:49]
	v_exp_f32_e32 v92, v92
	v_exp_f32_e32 v93, v93
	v_exp_f32_e32 v94, v94
	s_add_i32 s35, s15, -2
	s_lshl_b32 s5, s34, 13
	s_cmp_lt_u32 s15, s27
	s_cselect_b32 s10, s15, s29
	v_mfma_f32_32x32x16_bf16 v[18:33], v[12:15], v[214:217], v[18:33]
	v_exp_f32_e32 v95, v95
	v_exp_f32_e32 v96, v96
	v_exp_f32_e32 v97, v97
	s_lshl_b64 s[6:7], s[10:11], 16
	s_waitcnt vmcnt(0)
	v_mfma_f32_32x32x16_bf16 v[50:65], v[12:15], v[226:229], v[50:65]
	v_cvt_pk_bf16_f32 v222, v90, v91
	v_cvt_pk_bf16_f32 v223, v92, v93
	v_cvt_pk_bf16_f32 v224, v94, v95
	v_cvt_pk_bf16_f32 v225, v96, v97
	v_lshl_add_u64 v[6:7], v[116:117], 0, s[6:7]
	v_lshl_add_u64 v[8:9], v[118:119], 0, s[6:7]
	v_mfma_f32_32x32x16_bf16 v[34:49], v[222:225], v[164:167], v[34:49]
	v_lshrrev_b32_e32 v3, v1, v138
	s_add_i32 s6, s5, 0xffffe000
	v_lshlrev_b32_e32 v3, 4, v3
	s_cmp_lg_u32 s34, 0
	v_and_b32_e32 v4, 0xf0f0f0f0, v3
	v_mfma_f32_32x32x16_bf16 v[18:33], v[222:225], v[218:221], v[18:33]
	v_lshrrev_b32_e32 v3, v1, v139
	s_cselect_b32 s6, s6, 0x4000
	v_lshlrev_b32_e32 v3, 4, v3
	s_add_i32 s6, s20, s6
	v_and_b32_e32 v3, 0xf0f0f0f0, v3
	v_mfma_f32_32x32x16_bf16 v[50:65], v[222:225], v[226:229], v[50:65]
	s_cmp_lg_u32 s37, 0
	s_cbranch_scc1 .LBB0_946
	s_branch .Lpp_hb
.Lpp_bias:
	v_mfma_f32_32x32x16_bf16 v[82:97], v[198:201], v[110:113], v[82:97]
	v_mfma_f32_32x32x16_bf16 v[82:97], v[202:205], v[98:101], v[82:97]
	v_mfma_f32_32x32x16_bf16 v[82:97], v[206:209], v[102:105], v[82:97]
	v_mfma_f32_32x32x16_bf16 v[82:97], v[210:213], v[106:109], v[82:97]
	v_add_u32_e32 v3, s31, v148
	v_add_u32_e32 v4, 0x149fc, v3
	v_add_u32_e32 v6, 0x1497c, v3
	v_add_u32_e32 v8, 0x149f4, v3
	ds_read2_b32 v[4:5], v4 offset1:1
	ds_read2_b32 v[6:7], v6 offset1:1
	ds_read2_b32 v[8:9], v8 offset1:1
	v_add_u32_e32 v10, 0x14974, v3
	v_add_u32_e32 v12, 0x14954, v3
	s_waitcnt lgkmcnt(2)
	v_pk_add_f32 v[66:67], v[66:67], v[4:5] op_sel:[0,1] op_sel_hi:[1,0]
	s_waitcnt lgkmcnt(1)
	v_pk_add_f32 v[82:83], v[82:83], v[6:7] op_sel:[0,1] op_sel_hi:[1,0]
	s_waitcnt lgkmcnt(0)
	v_pk_add_f32 v[68:69], v[68:69], v[8:9] op_sel:[0,1] op_sel_hi:[1,0]
	v_add_u32_e32 v4, 0x149dc, v3
	v_add_u32_e32 v6, 0x1495c, v3
	v_add_u32_e32 v8, 0x149d4, v3
	ds_read2_b32 v[10:11], v10 offset1:1
	ds_read2_b32 v[4:5], v4 offset1:1
	ds_read2_b32 v[6:7], v6 offset1:1
	ds_read2_b32 v[8:9], v8 offset1:1
	ds_read2_b32 v[12:13], v12 offset1:1
	s_waitcnt lgkmcnt(3)
	v_pk_add_f32 v[70:71], v[70:71], v[4:5] op_sel:[0,1] op_sel_hi:[1,0]
	s_waitcnt lgkmcnt(2)
	v_pk_add_f32 v[86:87], v[86:87], v[6:7] op_sel:[0,1] op_sel_hi:[1,0]
	s_waitcnt lgkmcnt(1)
	v_pk_add_f32 v[72:73], v[72:73], v[8:9] op_sel:[0,1] op_sel_hi:[1,0]
	v_add_u32_e32 v4, 0x149bc, v3
	v_add_u32_e32 v6, 0x1493c, v3
	v_add_u32_e32 v8, 0x149b4, v3
	ds_read2_b32 v[4:5], v4 offset1:1
	ds_read2_b32 v[6:7], v6 offset1:1
	ds_read2_b32 v[8:9], v8 offset1:1
	v_pk_add_f32 v[84:85], v[84:85], v[10:11] op_sel:[0,1] op_sel_hi:[1,0]
	v_add_u32_e32 v10, 0x14934, v3
	s_waitcnt lgkmcnt(2)
	v_pk_add_f32 v[74:75], v[74:75], v[4:5] op_sel:[0,1] op_sel_hi:[1,0]
	s_waitcnt lgkmcnt(1)
	v_pk_add_f32 v[90:91], v[90:91], v[6:7] op_sel:[0,1] op_sel_hi:[1,0]
	s_waitcnt lgkmcnt(0)
	v_pk_add_f32 v[76:77], v[76:77], v[8:9] op_sel:[0,1] op_sel_hi:[1,0]
	v_add_u32_e32 v4, 0x1499c, v3
	v_add_u32_e32 v6, 0x1491c, v3
	v_add_u32_e32 v8, 0x14994, v3
	v_pk_add_f32 v[88:89], v[88:89], v[12:13] op_sel:[0,1] op_sel_hi:[1,0]
	ds_read2_b32 v[10:11], v10 offset1:1
	v_add_u32_e32 v3, 0x14914, v3
	ds_read2_b32 v[4:5], v4 offset1:1
	ds_read2_b32 v[6:7], v6 offset1:1
	ds_read2_b32 v[8:9], v8 offset1:1
	ds_read2_b32 v[12:13], v3 offset1:1
	s_waitcnt lgkmcnt(3)
	v_pk_add_f32 v[78:79], v[78:79], v[4:5] op_sel:[0,1] op_sel_hi:[1,0]
	v_pk_add_f32 v[92:93], v[92:93], v[10:11] op_sel:[0,1] op_sel_hi:[1,0]
	s_waitcnt lgkmcnt(2)
	v_pk_add_f32 v[94:95], v[94:95], v[6:7] op_sel:[0,1] op_sel_hi:[1,0]
	s_waitcnt lgkmcnt(1)
	v_pk_add_f32 v[80:81], v[80:81], v[8:9] op_sel:[0,1] op_sel_hi:[1,0]
	s_waitcnt lgkmcnt(0)
	v_pk_add_f32 v[96:97], v[96:97], v[12:13] op_sel:[0,1] op_sel_hi:[1,0]
	s_add_i32 s5, s34, 1
	s_cmp_lg_u32 s34, 2
	s_cselect_b32 s34, s5, 0
	s_addk_i32 s31, 0xff00
	s_add_i32 s15, s15, 1
	s_add_i32 s5, s30, s31
	s_add_i32 s33, s33, 64
	s_cmp_eq_u32 s5, 0
	s_cselect_b32 s37, 1, 0
	v_exp_f32_e32 v66, v66
	v_exp_f32_e32 v67, v67
	v_exp_f32_e32 v68, v68
	v_exp_f32_e32 v69, v69
	v_exp_f32_e32 v70, v70
	v_exp_f32_e32 v71, v71
	v_exp_f32_e32 v72, v72
	v_exp_f32_e32 v73, v73
	v_cvt_pk_bf16_f32 v4, v66, v67
	v_cvt_pk_bf16_f32 v5, v68, v69
	v_cvt_pk_bf16_f32 v6, v70, v71
	v_cvt_pk_bf16_f32 v7, v72, v73
	v_exp_f32_e32 v74, v74
	v_exp_f32_e32 v75, v75
	s_branch .Lpp_m9
